# gdn_chunk_prep: single-wave gate section before the barrier at s_setprio 2
# baseline (speedup 1.0000x reference)
.LBB0_365:
	s_or_b64 exec, exec, s[86:87]
	s_waitcnt vmcnt(59)
	v_lshlrev_b32_e32 v0, 16, v8
	v_cndmask_b32_e64 v1, 0, v0, s[44:45]
	s_waitcnt vmcnt(57)
	v_lshlrev_b32_e32 v0, 16, v9
	v_cndmask_b32_e64 v8, 0, v0, s[46:47]
	s_waitcnt vmcnt(55)
	v_lshlrev_b32_e32 v0, 16, v49
	v_cndmask_b32_e64 v9, 0, v0, s[48:49]
	s_waitcnt vmcnt(53)
	v_lshlrev_b32_e32 v0, 16, v50
	v_cndmask_b32_e64 v49, 0, v0, s[50:51]
	s_waitcnt vmcnt(50)
	v_lshlrev_b32_e32 v0, 16, v51
	v_cndmask_b32_e64 v50, 0, v0, s[52:53]
	s_waitcnt vmcnt(47)
	v_lshlrev_b32_e32 v0, 16, v52
	s_waitcnt vmcnt(3)
	v_mul_f32_e32 v2, v65, v70
	v_cndmask_b32_e64 v51, 0, v0, s[54:55]
	v_lshlrev_b32_e32 v0, 16, v53
	s_waitcnt vmcnt(2)
	v_fmac_f32_e32 v2, v1, v66
	v_cndmask_b32_e64 v52, 0, v0, s[56:57]
	v_lshlrev_b32_e32 v0, 16, v54
	s_waitcnt vmcnt(1)
	v_fmac_f32_e32 v2, v8, v67
	v_cndmask_b32_e64 v53, 0, v0, s[58:59]
	v_lshlrev_b32_e32 v0, 16, v55
	s_waitcnt vmcnt(0)
	s_load_dwordx2 s[2:3], s[36:37], 0x28
	v_mov_b32_e32 v216, v68
	v_mov_b32_e32 v217, 0
	v_lshl_add_u64 v[216:217], s[40:41], 0, v[216:217]
	v_lshlrev_b64 v[216:217], 7, v[216:217]
	v_lshl_add_u64 v[216:217], s[80:81], 0, v[216:217]
	s_lshl_b32 vcc_lo, s26, 2
	s_mov_b32 vcc_hi, 0
	v_lshl_add_u64 v[216:217], v[216:217], 0, vcc
	s_mov_b64 vcc, 0x10000000
	v_lshl_add_u64 v[216:217], v[216:217], 0, vcc
	global_load_dword v200, v[216:217], off offset:16
	global_load_dword v201, v[216:217], off
	s_or_b32 vcc_lo, s26, s94
	s_lshl_b32 vcc_lo, vcc_lo, 2
	s_add_u32 s92, s92, vcc_lo
	s_addc_u32 s93, s93, 0
	global_load_dword v202, v129, s[92:93]
	s_mov_b64 vcc, 0x1000
	v_lshl_add_u64 v[212:213], v[6:7], 0, vcc
	s_mov_b64 vcc, 0x2000
	v_lshl_add_u64 v[214:215], v[6:7], 0, vcc
	global_load_dword v204, v[6:7], off offset:1024
	global_load_dword v205, v[212:213], off
	global_load_dword v206, v[212:213], off offset:3072
	global_load_dword v207, v[214:215], off offset:2048
	global_load_dword v208, v[6:7], off offset:2048
	global_load_dword v209, v[212:213], off offset:1024
	global_load_dword v210, v[214:215], off
	global_load_dword v211, v[214:215], off offset:3072
	s_waitcnt lgkmcnt(0)
	s_or_b32 vcc_lo, s26, s94
	s_lshl_b32 vcc_lo, vcc_lo, 2
	s_add_u32 s2, s2, vcc_lo
	s_addc_u32 s3, s3, 0
	global_load_dword v203, v129, s[2:3]
	v_fmac_f32_e32 v2, v9, v69
	v_cndmask_b32_e64 v54, 0, v0, s[60:61]
	v_lshlrev_b32_e32 v0, 16, v56
	v_mul_f32_e32 v3, 0xbfb8aa3b, v2
	v_cndmask_b32_e64 v55, 0, v0, s[62:63]
	v_lshlrev_b32_e32 v0, 16, v57
	v_exp_f32_e32 v3, v3
	v_cndmask_b32_e64 v56, 0, v0, s[64:65]
	v_lshlrev_b32_e32 v0, 16, v58
	v_cndmask_b32_e64 v57, 0, v0, s[66:67]
	v_lshlrev_b32_e32 v0, 16, v59
	v_cndmask_b32_e64 v58, 0, v0, s[68:69]
	v_lshlrev_b32_e32 v0, 16, v60
	v_cndmask_b32_e64 v59, 0, v0, s[70:71]
	v_lshlrev_b32_e32 v0, 16, v61
	v_add_f32_e32 v3, 1.0, v3
	v_cndmask_b32_e64 v60, 0, v0, s[72:73]
	v_lshlrev_b32_e32 v0, 16, v62
	v_rcp_f32_e32 v3, v3
	v_cndmask_b32_e64 v61, 0, v0, s[74:75]
	v_lshlrev_b32_e32 v0, 16, v63
	s_and_b32 s2, s90, 0xfffffc00
	s_lshl_b32 s3, s26, 8
	v_cndmask_b32_e64 v62, 0, v0, s[76:77]
	v_lshlrev_b32_e32 v0, 16, v64
	s_or_b32 s2, s3, s2
	v_cndmask_b32_e64 v63, 0, v0, s[78:79]
	v_lshlrev_b32_e32 v0, 2, v34
	s_or_b32 s86, s2, s27
	v_mul_f32_e32 v64, v2, v3
	v_mad_u64_u32 v[2:3], s[2:3], v5, s33, v[0:1]
	v_mul_f32_e32 v3, v8, v66
	v_fmac_f32_e32 v3, v1, v65
	v_fmac_f32_e32 v3, v9, v67
	v_fmac_f32_e32 v3, v49, v69
	v_mul_f32_e32 v1, 0xbfb8aa3b, v3
	v_exp_f32_e32 v1, v1
	v_lshlrev_b32_e32 v30, 16, v30
	v_lshlrev_b32_e32 v29, 16, v29
	v_cndmask_b32_e64 v30, 0, v30, s[44:45]
	v_add_f32_e32 v1, 1.0, v1
	v_rcp_f32_e32 v1, v1
	v_cndmask_b32_e64 v29, 0, v29, s[42:43]
	v_lshlrev_b32_e32 v31, 16, v31
	v_cndmask_b32_e64 v31, 0, v31, s[46:47]
	v_mul_f32_e32 v1, v3, v1
	ds_write2_b32 v2, v64, v1 offset1:65
	v_mul_f32_e32 v1, v9, v66
	v_fmac_f32_e32 v1, v8, v65
	v_fmac_f32_e32 v1, v49, v67
	v_fmac_f32_e32 v1, v50, v69
	v_mul_f32_e32 v3, 0xbfb8aa3b, v1
	v_exp_f32_e32 v3, v3
	v_lshlrev_b32_e32 v32, 16, v32
	v_cndmask_b32_e64 v32, 0, v32, s[48:49]
	v_lshlrev_b32_e32 v33, 16, v33
	v_add_f32_e32 v3, 1.0, v3
	v_rcp_f32_e32 v3, v3
	v_cndmask_b32_e64 v33, 0, v33, s[50:51]
	v_lshlrev_b32_e32 v35, 16, v35
	v_cndmask_b32_e64 v35, 0, v35, s[52:53]
	v_mul_f32_e32 v1, v1, v3
	v_mul_f32_e32 v3, v49, v66
	v_fmac_f32_e32 v3, v9, v65
	v_fmac_f32_e32 v3, v50, v67
	v_fmac_f32_e32 v3, v51, v69
	v_mul_f32_e32 v5, 0xbfb8aa3b, v3
	v_exp_f32_e32 v5, v5
	v_lshlrev_b32_e32 v36, 16, v36
	v_cndmask_b32_e64 v36, 0, v36, s[54:55]
	v_lshlrev_b32_e32 v37, 16, v37
	v_add_f32_e32 v5, 1.0, v5
	v_rcp_f32_e32 v5, v5
	v_cndmask_b32_e64 v37, 0, v37, s[56:57]
	v_lshlrev_b32_e32 v38, 16, v38
	v_cndmask_b32_e64 v38, 0, v38, s[58:59]
	v_mul_f32_e32 v3, v3, v5
	ds_write2_b32 v2, v1, v3 offset0:130 offset1:195
	v_mul_f32_e32 v1, v50, v66
	v_fmac_f32_e32 v1, v49, v65
	v_fmac_f32_e32 v1, v51, v67
	v_fmac_f32_e32 v1, v52, v69
	v_mul_f32_e32 v3, 0xbfb8aa3b, v1
	v_exp_f32_e32 v3, v3
	v_lshlrev_b32_e32 v39, 16, v39
	v_cndmask_b32_e64 v39, 0, v39, s[60:61]
	v_lshlrev_b32_e32 v40, 16, v40
	v_add_f32_e32 v3, 1.0, v3
	v_rcp_f32_e32 v3, v3
	v_cndmask_b32_e64 v40, 0, v40, s[62:63]
	v_lshlrev_b32_e32 v41, 16, v41
	v_cndmask_b32_e64 v41, 0, v41, s[64:65]
	v_mul_f32_e32 v1, v1, v3
	v_mul_f32_e32 v3, v51, v66
	v_fmac_f32_e32 v3, v50, v65
	v_fmac_f32_e32 v3, v52, v67
	v_fmac_f32_e32 v3, v53, v69
	v_mul_f32_e32 v5, 0xbfb8aa3b, v3
	v_exp_f32_e32 v5, v5
	v_lshlrev_b32_e32 v42, 16, v42
	v_cndmask_b32_e64 v42, 0, v42, s[66:67]
	v_lshlrev_b32_e32 v43, 16, v43
	v_add_f32_e32 v5, 1.0, v5
	v_rcp_f32_e32 v5, v5
	v_cndmask_b32_e64 v43, 0, v43, s[68:69]
	v_lshlrev_b32_e32 v44, 16, v44
	v_cndmask_b32_e64 v44, 0, v44, s[70:71]
	v_mul_f32_e32 v3, v3, v5
	v_add_u32_e32 v5, 0x400, v2
	ds_write2_b32 v5, v1, v3 offset0:4 offset1:69
	v_mul_f32_e32 v1, v52, v66
	v_fmac_f32_e32 v1, v51, v65
	v_fmac_f32_e32 v1, v53, v67
	v_fmac_f32_e32 v1, v54, v69
	v_mul_f32_e32 v3, 0xbfb8aa3b, v1
	v_exp_f32_e32 v3, v3
	v_lshlrev_b32_e32 v45, 16, v45
	v_cndmask_b32_e64 v45, 0, v45, s[72:73]
	v_lshlrev_b32_e32 v46, 16, v46
	v_add_f32_e32 v3, 1.0, v3
	v_rcp_f32_e32 v3, v3
	v_cndmask_b32_e64 v46, 0, v46, s[74:75]
	v_lshlrev_b32_e32 v47, 16, v47
	v_cndmask_b32_e64 v47, 0, v47, s[76:77]
	v_mul_f32_e32 v1, v1, v3
	v_mul_f32_e32 v3, v53, v66
	v_fmac_f32_e32 v3, v52, v65
	v_fmac_f32_e32 v3, v54, v67
	v_fmac_f32_e32 v3, v55, v69
	v_mul_f32_e32 v8, 0xbfb8aa3b, v3
	v_exp_f32_e32 v8, v8
	v_lshlrev_b32_e32 v48, 16, v48
	v_cndmask_b32_e64 v48, 0, v48, s[78:79]
	s_ashr_i32 s87, s86, 31
	v_add_f32_e32 v8, 1.0, v8
	v_rcp_f32_e32 v8, v8
	s_nop 0
	v_mul_f32_e32 v3, v3, v8
	ds_write2_b32 v5, v1, v3 offset0:134 offset1:199
	v_mul_f32_e32 v1, v54, v66
	v_fmac_f32_e32 v1, v53, v65
	v_fmac_f32_e32 v1, v55, v67
	v_fmac_f32_e32 v1, v56, v69
	v_mul_f32_e32 v3, 0xbfb8aa3b, v1
	v_exp_f32_e32 v3, v3
	s_nop 0
	v_add_f32_e32 v3, 1.0, v3
	v_rcp_f32_e32 v3, v3
	s_nop 0
	v_mul_f32_e32 v1, v1, v3
	v_mul_f32_e32 v3, v55, v66
	v_fmac_f32_e32 v3, v54, v65
	v_fmac_f32_e32 v3, v56, v67
	v_fmac_f32_e32 v3, v57, v69
	v_mul_f32_e32 v5, 0xbfb8aa3b, v3
	v_exp_f32_e32 v5, v5
	s_nop 0
	v_add_f32_e32 v5, 1.0, v5
	v_rcp_f32_e32 v5, v5
	s_nop 0
	v_mul_f32_e32 v3, v3, v5
	v_add_u32_e32 v5, 0x800, v2
	ds_write2_b32 v5, v1, v3 offset0:8 offset1:73
	v_mul_f32_e32 v1, v56, v66
	v_fmac_f32_e32 v1, v55, v65
	v_fmac_f32_e32 v1, v57, v67
	v_fmac_f32_e32 v1, v58, v69
	v_mul_f32_e32 v3, 0xbfb8aa3b, v1
	v_exp_f32_e32 v3, v3
	s_nop 0
	v_add_f32_e32 v3, 1.0, v3
	v_rcp_f32_e32 v3, v3
	s_nop 0
	v_mul_f32_e32 v1, v1, v3
	v_mul_f32_e32 v3, v57, v66
	v_fmac_f32_e32 v3, v56, v65
	v_fmac_f32_e32 v3, v58, v67
	v_fmac_f32_e32 v3, v59, v69
	v_mul_f32_e32 v8, 0xbfb8aa3b, v3
	v_exp_f32_e32 v8, v8
	s_nop 0
	v_add_f32_e32 v8, 1.0, v8
	v_rcp_f32_e32 v8, v8
	s_nop 0
	v_mul_f32_e32 v3, v3, v8
	ds_write2_b32 v5, v1, v3 offset0:138 offset1:203
	v_mul_f32_e32 v1, v58, v66
	v_fmac_f32_e32 v1, v57, v65
	v_fmac_f32_e32 v1, v59, v67
	v_fmac_f32_e32 v1, v60, v69
	v_mul_f32_e32 v3, 0xbfb8aa3b, v1
	v_exp_f32_e32 v3, v3
	s_nop 0
	v_add_f32_e32 v3, 1.0, v3
	v_rcp_f32_e32 v3, v3
	s_nop 0
	v_mul_f32_e32 v1, v1, v3
	v_mul_f32_e32 v3, v59, v66
	v_fmac_f32_e32 v3, v58, v65
	v_fmac_f32_e32 v3, v60, v67
	v_fmac_f32_e32 v3, v61, v69
	v_mul_f32_e32 v5, 0xbfb8aa3b, v3
	v_exp_f32_e32 v5, v5
	s_nop 0
	v_add_f32_e32 v5, 1.0, v5
	v_rcp_f32_e32 v5, v5
	s_nop 0
	v_mul_f32_e32 v3, v3, v5
	v_add_u32_e32 v5, 0xc00, v2
	ds_write2_b32 v5, v1, v3 offset0:12 offset1:77
	v_mul_f32_e32 v1, v60, v66
	v_fmac_f32_e32 v1, v59, v65
	v_fmac_f32_e32 v1, v61, v67
	v_fmac_f32_e32 v1, v62, v69
	v_mul_f32_e32 v3, 0xbfb8aa3b, v1
	v_exp_f32_e32 v3, v3
	s_nop 0
	v_add_f32_e32 v3, 1.0, v3
	v_rcp_f32_e32 v3, v3
	s_nop 0
	v_mul_f32_e32 v1, v1, v3
	ds_write_b32 v2, v1 offset:3640
	v_mul_f32_e32 v1, v61, v66
	v_fmac_f32_e32 v1, v60, v65
	v_fmac_f32_e32 v1, v62, v67
	v_fmac_f32_e32 v1, v63, v69
	v_mul_f32_e32 v3, 0xbfb8aa3b, v1
	v_exp_f32_e32 v3, v3
	s_nop 0
	v_add_f32_e32 v3, 1.0, v3
	v_rcp_f32_e32 v3, v3
	s_nop 0
	v_mul_f32_e32 v1, v1, v3
	v_mad_u64_u32 v[4:5], s[2:3], v4, s33, v[0:1]
	s_mov_b64 s[2:3], 0x400
	ds_write_b32 v4, v1
	v_lshl_add_u64 v[8:9], v[6:7], 0, s[2:3]
	s_movk_i32 s2, 0x1000
	s_waitcnt vmcnt(0)
	v_add_co_u32_e32 v8, vcc, s2, v6
	s_movk_i32 s2, 0x2000
	s_nop 0
	v_addc_co_u32_e32 v9, vcc, 0, v7, vcc
	v_add_co_u32_e32 v8, vcc, s2, v6
	v_mul_f32_e32 v50, v30, v205
	v_addc_co_u32_e32 v9, vcc, 0, v7, vcc
	v_fmac_f32_e32 v50, v29, v204
	s_mov_b64 vcc, 0x800
	v_fmac_f32_e32 v50, v31, v206
	v_fmac_f32_e32 v50, v32, v207
	v_mul_f32_e32 v29, 0xbfb8aa3b, v50
	v_exp_f32_e32 v29, v29
	s_nop 0
	v_add_f32_e32 v29, 1.0, v29
	v_rcp_f32_e32 v29, v29
	s_nop 0
	v_mul_f32_e32 v29, v50, v29
	v_mul_f32_e32 v50, v31, v205
	v_fmac_f32_e32 v50, v30, v204
	v_fmac_f32_e32 v50, v32, v206
	v_fmac_f32_e32 v50, v33, v207
	v_mul_f32_e32 v30, 0xbfb8aa3b, v50
	v_exp_f32_e32 v30, v30
	s_nop 0
	v_add_f32_e32 v30, 1.0, v30
	v_rcp_f32_e32 v30, v30
	s_nop 0
	v_mul_f32_e32 v30, v50, v30
	v_add_u32_e32 v50, 0x4000, v2
	ds_write2_b32 v50, v29, v30 offset0:64 offset1:129
	v_mul_f32_e32 v29, v32, v205
	v_fmac_f32_e32 v29, v31, v204
	v_fmac_f32_e32 v29, v33, v206
	v_fmac_f32_e32 v29, v35, v207
	v_mul_f32_e32 v30, 0xbfb8aa3b, v29
	v_exp_f32_e32 v30, v30
	s_nop 0
	v_add_f32_e32 v30, 1.0, v30
	v_rcp_f32_e32 v30, v30
	s_nop 0
	v_mul_f32_e32 v29, v29, v30
	v_mul_f32_e32 v30, v33, v205
	v_fmac_f32_e32 v30, v32, v204
	v_fmac_f32_e32 v30, v35, v206
	v_fmac_f32_e32 v30, v36, v207
	v_mul_f32_e32 v31, 0xbfb8aa3b, v30
	v_exp_f32_e32 v31, v31
	s_nop 0
	v_add_f32_e32 v31, 1.0, v31
	v_rcp_f32_e32 v31, v31
	s_nop 0
	v_mul_f32_e32 v30, v30, v31
	v_add_u32_e32 v31, 0x4200, v2
	ds_write2_b32 v31, v29, v30 offset0:66 offset1:131
	v_mul_f32_e32 v29, v35, v205
	v_fmac_f32_e32 v29, v33, v204
	v_fmac_f32_e32 v29, v36, v206
	v_fmac_f32_e32 v29, v37, v207
	v_mul_f32_e32 v30, 0xbfb8aa3b, v29
	v_exp_f32_e32 v30, v30
	s_nop 0
	v_add_f32_e32 v30, 1.0, v30
	v_rcp_f32_e32 v30, v30
	s_nop 0
	v_mul_f32_e32 v29, v29, v30
	v_mul_f32_e32 v30, v36, v205
	v_fmac_f32_e32 v30, v35, v204
	v_fmac_f32_e32 v30, v37, v206
	v_fmac_f32_e32 v30, v38, v207
	v_mul_f32_e32 v31, 0xbfb8aa3b, v30
	v_exp_f32_e32 v31, v31
	s_nop 0
	v_add_f32_e32 v31, 1.0, v31
	v_rcp_f32_e32 v31, v31
	s_nop 0
	v_mul_f32_e32 v30, v30, v31
	v_add_u32_e32 v31, 0x4400, v2
	ds_write2_b32 v31, v29, v30 offset0:68 offset1:133
	v_mul_f32_e32 v29, v37, v205
	v_fmac_f32_e32 v29, v36, v204
	v_fmac_f32_e32 v29, v38, v206
	v_fmac_f32_e32 v29, v39, v207
	v_mul_f32_e32 v30, 0xbfb8aa3b, v29
	v_exp_f32_e32 v30, v30
	s_nop 0
	v_add_f32_e32 v30, 1.0, v30
	v_rcp_f32_e32 v30, v30
	s_nop 0
	v_mul_f32_e32 v29, v29, v30
	v_mul_f32_e32 v30, v38, v205
	v_fmac_f32_e32 v30, v37, v204
	v_fmac_f32_e32 v30, v39, v206
	v_fmac_f32_e32 v30, v40, v207
	v_mul_f32_e32 v31, 0xbfb8aa3b, v30
	v_exp_f32_e32 v31, v31
	s_nop 0
	v_add_f32_e32 v31, 1.0, v31
	v_rcp_f32_e32 v31, v31
	s_nop 0
	v_mul_f32_e32 v30, v30, v31
	v_add_u32_e32 v31, 0x4600, v2
	ds_write2_b32 v31, v29, v30 offset0:70 offset1:135
	v_mul_f32_e32 v29, v39, v205
	v_fmac_f32_e32 v29, v38, v204
	v_fmac_f32_e32 v29, v40, v206
	v_fmac_f32_e32 v29, v41, v207
	v_mul_f32_e32 v30, 0xbfb8aa3b, v29
	v_exp_f32_e32 v30, v30
	s_nop 0
	v_add_f32_e32 v30, 1.0, v30
	v_rcp_f32_e32 v30, v30
	s_nop 0
	v_mul_f32_e32 v29, v29, v30
	v_mul_f32_e32 v30, v40, v205
	v_fmac_f32_e32 v30, v39, v204
	v_fmac_f32_e32 v30, v41, v206
	v_fmac_f32_e32 v30, v42, v207
	v_mul_f32_e32 v31, 0xbfb8aa3b, v30
	v_exp_f32_e32 v31, v31
	s_nop 0
	v_add_f32_e32 v31, 1.0, v31
	v_rcp_f32_e32 v31, v31
	s_nop 0
	v_mul_f32_e32 v30, v30, v31
	v_add_u32_e32 v31, 0x4800, v2
	ds_write2_b32 v31, v29, v30 offset0:72 offset1:137
	v_mul_f32_e32 v29, v41, v205
	v_fmac_f32_e32 v29, v40, v204
	v_fmac_f32_e32 v29, v42, v206
	v_fmac_f32_e32 v29, v43, v207
	v_mul_f32_e32 v30, 0xbfb8aa3b, v29
	v_exp_f32_e32 v30, v30
	s_nop 0
	v_add_f32_e32 v30, 1.0, v30
	v_rcp_f32_e32 v30, v30
	s_nop 0
	v_mul_f32_e32 v29, v29, v30
	v_mul_f32_e32 v30, v42, v205
	v_fmac_f32_e32 v30, v41, v204
	v_fmac_f32_e32 v30, v43, v206
	v_fmac_f32_e32 v30, v44, v207
	v_mul_f32_e32 v31, 0xbfb8aa3b, v30
	v_exp_f32_e32 v31, v31
	s_nop 0
	v_add_f32_e32 v31, 1.0, v31
	v_rcp_f32_e32 v31, v31
	s_nop 0
	v_mul_f32_e32 v30, v30, v31
	v_add_u32_e32 v31, 0x4a00, v2
	ds_write2_b32 v31, v29, v30 offset0:74 offset1:139
	v_mul_f32_e32 v29, v43, v205
	v_fmac_f32_e32 v29, v42, v204
	v_fmac_f32_e32 v29, v44, v206
	v_fmac_f32_e32 v29, v45, v207
	v_mul_f32_e32 v30, 0xbfb8aa3b, v29
	v_exp_f32_e32 v30, v30
	s_nop 0
	v_add_f32_e32 v30, 1.0, v30
	v_rcp_f32_e32 v30, v30
	s_nop 0
	v_mul_f32_e32 v29, v29, v30
	v_mul_f32_e32 v30, v44, v205
	v_fmac_f32_e32 v30, v43, v204
	v_fmac_f32_e32 v30, v45, v206
	v_fmac_f32_e32 v30, v46, v207
	v_mul_f32_e32 v31, 0xbfb8aa3b, v30
	v_exp_f32_e32 v31, v31
	s_nop 0
	v_add_f32_e32 v31, 1.0, v31
	v_rcp_f32_e32 v31, v31
	s_nop 0
	v_mul_f32_e32 v30, v30, v31
	v_add_u32_e32 v31, 0x4c00, v2
	ds_write2_b32 v31, v29, v30 offset0:76 offset1:141
	v_mul_f32_e32 v29, v45, v205
	v_mul_f32_e32 v3, v46, v205
	v_fmac_f32_e32 v29, v44, v204
	v_fmac_f32_e32 v3, v45, v204
	v_fmac_f32_e32 v29, v46, v206
	v_fmac_f32_e32 v3, v47, v206
	v_fmac_f32_e32 v29, v47, v207
	v_fmac_f32_e32 v3, v48, v207
	v_mul_f32_e32 v30, 0xbfb8aa3b, v29
	v_mul_f32_e32 v1, 0xbfb8aa3b, v3
	v_exp_f32_e32 v30, v30
	v_exp_f32_e32 v1, v1
	v_add_f32_e32 v30, 1.0, v30
	v_add_f32_e32 v1, 1.0, v1
	v_rcp_f32_e32 v30, v30
	v_rcp_f32_e32 v1, v1
	v_mul_f32_e32 v29, v29, v30
	v_mul_f32_e32 v1, v3, v1
	ds_write_b32 v2, v29 offset:20280
	ds_write_b32 v4, v1 offset:16640
	v_lshl_add_u64 v[30:31], v[6:7], 0, vcc
	s_waitcnt vmcnt(0)
	s_nop 0
	v_lshlrev_b32_e32 v8, 16, v11
	v_lshlrev_b32_e32 v7, 16, v10
	v_cndmask_b32_e64 v8, 0, v8, s[44:45]
	v_cndmask_b32_e64 v7, 0, v7, s[42:43]
	v_lshlrev_b32_e32 v9, 16, v12
	v_lshlrev_b32_e32 v11, 16, v14
	v_lshlrev_b32_e32 v14, 16, v17
	v_lshlrev_b32_e32 v17, 16, v20
	v_lshlrev_b32_e32 v20, 16, v23
	v_lshlrev_b32_e32 v23, 16, v26
	v_cndmask_b32_e64 v9, 0, v9, s[46:47]
	v_lshlrev_b32_e32 v10, 16, v13
	v_cndmask_b32_e64 v10, 0, v10, s[48:49]
	v_cndmask_b32_e64 v11, 0, v11, s[50:51]
	v_lshlrev_b32_e32 v12, 16, v15
	v_cndmask_b32_e64 v12, 0, v12, s[52:53]
	v_lshlrev_b32_e32 v13, 16, v16
	v_cndmask_b32_e64 v13, 0, v13, s[54:55]
	v_cndmask_b32_e64 v14, 0, v14, s[56:57]
	v_lshlrev_b32_e32 v15, 16, v18
	v_cndmask_b32_e64 v15, 0, v15, s[58:59]
	v_lshlrev_b32_e32 v16, 16, v19
	v_cndmask_b32_e64 v16, 0, v16, s[60:61]
	v_cndmask_b32_e64 v17, 0, v17, s[62:63]
	v_lshlrev_b32_e32 v18, 16, v21
	v_cndmask_b32_e64 v18, 0, v18, s[64:65]
	v_lshlrev_b32_e32 v19, 16, v22
	v_cndmask_b32_e64 v19, 0, v19, s[66:67]
	v_cndmask_b32_e64 v20, 0, v20, s[68:69]
	v_lshlrev_b32_e32 v21, 16, v24
	v_cndmask_b32_e64 v21, 0, v21, s[70:71]
	v_lshlrev_b32_e32 v22, 16, v25
	v_cndmask_b32_e64 v22, 0, v22, s[72:73]
	v_cndmask_b32_e64 v23, 0, v23, s[74:75]
	v_lshlrev_b32_e32 v24, 16, v27
	v_cndmask_b32_e64 v24, 0, v24, s[76:77]
	v_lshlrev_b32_e32 v25, 16, v28
	v_cndmask_b32_e64 v25, 0, v25, s[78:79]
	v_cmp_lt_i32_e64 s[42:43], 63, v68
	v_cmp_gt_i32_e64 s[44:45], 64, v68
	v_mul_f32_e32 v26, v8, v209
	v_fmac_f32_e32 v26, v7, v208
	v_fmac_f32_e32 v26, v9, v210
	v_fmac_f32_e32 v26, v10, v211
	v_mul_f32_e32 v7, 0xbfb8aa3b, v26
	v_exp_f32_e32 v7, v7
	s_nop 0
	v_add_f32_e32 v7, 1.0, v7
	v_rcp_f32_e32 v7, v7
	s_nop 0
	v_mul_f32_e32 v7, v26, v7
	v_mul_f32_e32 v26, v9, v209
	v_fmac_f32_e32 v26, v8, v208
	v_fmac_f32_e32 v26, v10, v210
	v_fmac_f32_e32 v26, v11, v211
	v_mul_f32_e32 v8, 0xbfb8aa3b, v26
	v_exp_f32_e32 v8, v8
	s_nop 0
	v_add_f32_e32 v8, 1.0, v8
	v_rcp_f32_e32 v8, v8
	s_nop 0
	v_mul_f32_e32 v8, v26, v8
	v_add_u32_e32 v26, 0x8000, v2
	ds_write2_b32 v26, v7, v8 offset0:128 offset1:193
	v_mul_f32_e32 v7, v10, v209
	v_fmac_f32_e32 v7, v9, v208
	v_fmac_f32_e32 v7, v11, v210
	v_fmac_f32_e32 v7, v12, v211
	v_mul_f32_e32 v8, 0xbfb8aa3b, v7
	v_exp_f32_e32 v8, v8
	s_nop 0
	v_add_f32_e32 v8, 1.0, v8
	v_rcp_f32_e32 v8, v8
	s_nop 0
	v_mul_f32_e32 v7, v7, v8
	v_mul_f32_e32 v8, v11, v209
	v_fmac_f32_e32 v8, v10, v208
	v_fmac_f32_e32 v8, v12, v210
	v_fmac_f32_e32 v8, v13, v211
	v_mul_f32_e32 v9, 0xbfb8aa3b, v8
	v_exp_f32_e32 v9, v9
	s_nop 0
	v_add_f32_e32 v9, 1.0, v9
	v_rcp_f32_e32 v9, v9
	s_nop 0
	v_mul_f32_e32 v8, v8, v9
	v_add_u32_e32 v9, 0x8400, v2
	ds_write2_b32 v9, v7, v8 offset0:2 offset1:67
	v_mul_f32_e32 v7, v12, v209
	v_fmac_f32_e32 v7, v11, v208
	v_fmac_f32_e32 v7, v13, v210
	v_fmac_f32_e32 v7, v14, v211
	v_mul_f32_e32 v8, 0xbfb8aa3b, v7
	v_exp_f32_e32 v8, v8
	s_nop 0
	v_add_f32_e32 v8, 1.0, v8
	v_rcp_f32_e32 v8, v8
	s_nop 0
	v_mul_f32_e32 v7, v7, v8
	v_mul_f32_e32 v8, v13, v209
	v_fmac_f32_e32 v8, v12, v208
	v_fmac_f32_e32 v8, v14, v210
	v_fmac_f32_e32 v8, v15, v211
	v_mul_f32_e32 v10, 0xbfb8aa3b, v8
	v_exp_f32_e32 v10, v10
	s_nop 0
	v_add_f32_e32 v10, 1.0, v10
	v_rcp_f32_e32 v10, v10
	s_nop 0
	v_mul_f32_e32 v8, v8, v10
	ds_write2_b32 v9, v7, v8 offset0:132 offset1:197
	v_mul_f32_e32 v7, v14, v209
	v_fmac_f32_e32 v7, v13, v208
	v_fmac_f32_e32 v7, v15, v210
	v_fmac_f32_e32 v7, v16, v211
	v_mul_f32_e32 v8, 0xbfb8aa3b, v7
	v_exp_f32_e32 v8, v8
	s_nop 0
	v_add_f32_e32 v8, 1.0, v8
	v_rcp_f32_e32 v8, v8
	s_nop 0
	v_mul_f32_e32 v7, v7, v8
	v_mul_f32_e32 v8, v15, v209
	v_fmac_f32_e32 v8, v14, v208
	v_fmac_f32_e32 v8, v16, v210
	v_fmac_f32_e32 v8, v17, v211
	v_mul_f32_e32 v9, 0xbfb8aa3b, v8
	v_exp_f32_e32 v9, v9
	s_nop 0
	v_add_f32_e32 v9, 1.0, v9
	v_rcp_f32_e32 v9, v9
	s_nop 0
	v_mul_f32_e32 v8, v8, v9
	v_add_u32_e32 v9, 0x8800, v2
	ds_write2_b32 v9, v7, v8 offset0:6 offset1:71
	v_mul_f32_e32 v7, v16, v209
	v_fmac_f32_e32 v7, v15, v208
	v_fmac_f32_e32 v7, v17, v210
	v_fmac_f32_e32 v7, v18, v211
	v_mul_f32_e32 v8, 0xbfb8aa3b, v7
	v_exp_f32_e32 v8, v8
	s_nop 0
	v_add_f32_e32 v8, 1.0, v8
	v_rcp_f32_e32 v8, v8
	s_nop 0
	v_mul_f32_e32 v7, v7, v8
	v_mul_f32_e32 v8, v17, v209
	v_fmac_f32_e32 v8, v16, v208
	v_fmac_f32_e32 v8, v18, v210
	v_fmac_f32_e32 v8, v19, v211
	v_mul_f32_e32 v10, 0xbfb8aa3b, v8
	v_exp_f32_e32 v10, v10
	s_nop 0
	v_add_f32_e32 v10, 1.0, v10
	v_rcp_f32_e32 v10, v10
	s_nop 0
	v_mul_f32_e32 v8, v8, v10
	ds_write2_b32 v9, v7, v8 offset0:136 offset1:201
	v_mul_f32_e32 v7, v18, v209
	v_fmac_f32_e32 v7, v17, v208
	v_fmac_f32_e32 v7, v19, v210
	v_fmac_f32_e32 v7, v20, v211
	v_mul_f32_e32 v8, 0xbfb8aa3b, v7
	v_exp_f32_e32 v8, v8
	s_nop 0
	v_add_f32_e32 v8, 1.0, v8
	v_rcp_f32_e32 v8, v8
	s_nop 0
	v_mul_f32_e32 v7, v7, v8
	v_mul_f32_e32 v8, v19, v209
	v_fmac_f32_e32 v8, v18, v208
	v_fmac_f32_e32 v8, v20, v210
	v_fmac_f32_e32 v8, v21, v211
	v_mul_f32_e32 v9, 0xbfb8aa3b, v8
	v_exp_f32_e32 v9, v9
	s_nop 0
	v_add_f32_e32 v9, 1.0, v9
	v_rcp_f32_e32 v9, v9
	s_nop 0
	v_mul_f32_e32 v8, v8, v9
	v_add_u32_e32 v9, 0x8c00, v2
	ds_write2_b32 v9, v7, v8 offset0:10 offset1:75
	v_mul_f32_e32 v7, v20, v209
	v_fmac_f32_e32 v7, v19, v208
	v_fmac_f32_e32 v7, v21, v210
	v_fmac_f32_e32 v7, v22, v211
	v_mul_f32_e32 v8, 0xbfb8aa3b, v7
	v_exp_f32_e32 v8, v8
	s_nop 0
	v_add_f32_e32 v8, 1.0, v8
	v_rcp_f32_e32 v8, v8
	s_nop 0
	v_mul_f32_e32 v7, v7, v8
	v_mul_f32_e32 v8, v21, v209
	v_fmac_f32_e32 v8, v20, v208
	v_fmac_f32_e32 v8, v22, v210
	v_fmac_f32_e32 v8, v23, v211
	v_mul_f32_e32 v10, 0xbfb8aa3b, v8
	v_exp_f32_e32 v10, v10
	s_nop 0
	v_add_f32_e32 v10, 1.0, v10
	v_rcp_f32_e32 v10, v10
	s_nop 0
	v_mul_f32_e32 v8, v8, v10
	ds_write2_b32 v9, v7, v8 offset0:140 offset1:205
	v_mul_f32_e32 v7, v22, v209
	v_fmac_f32_e32 v7, v21, v208
	v_fmac_f32_e32 v7, v23, v210
	v_fmac_f32_e32 v7, v24, v211
	v_mul_f32_e32 v8, 0xbfb8aa3b, v7
	v_exp_f32_e32 v8, v8
	s_nop 0
	v_add_f32_e32 v8, 1.0, v8
	v_rcp_f32_e32 v8, v8
	s_nop 0
	v_mul_f32_e32 v7, v7, v8
	ds_write_b32 v2, v7 offset:36920
	v_mul_f32_e32 v2, v23, v209
	v_fmac_f32_e32 v2, v22, v208
	v_fmac_f32_e32 v2, v24, v210
	v_fmac_f32_e32 v2, v25, v211
	v_mul_f32_e32 v1, 0xbfb8aa3b, v2
	v_exp_f32_e32 v1, v1
	s_nop 0
	v_add_f32_e32 v1, 1.0, v1
	v_rcp_f32_e32 v1, v1
	s_nop 0
	v_mul_f32_e32 v1, v2, v1
	ds_write_b32 v4, v1 offset:33280
	v_lshlrev_b32_e32 v1, 2, v68
	v_mov_b32_e32 v3, v210
	v_mov_b32_e32 v5, v209
	v_mov_b32_e32 v6, v211
	v_mov_b32_e32 v49, v207
	s_and_saveexec_b64 s[46:47], s[44:45]
	s_cbranch_execz .LBB0_368
	s_setprio 2
	v_ashrrev_i32_e32 v69, 31, v68
	v_lshl_add_u64 v[2:3], s[40:41], 0, v[68:69]
	v_lshlrev_b64 v[2:3], 7, v[2:3]
	v_lshl_add_u64 v[2:3], s[80:81], 0, v[2:3]
	s_lshl_b32 s84, s26, 2
	v_lshl_add_u64 v[2:3], v[2:3], 0, s[84:85]
	s_or_b32 s84, s26, s94
	s_mov_b64 s[2:3], 0x10000000
	s_lshl_b64 s[40:41], s[84:85], 2
	v_lshl_add_u64 v[4:5], v[2:3], 0, s[2:3]
	s_waitcnt lgkmcnt(0)
	s_add_u32 s2, s50, s40
	v_add_co_u32_e32 v2, vcc, 0x10000000, v2
	s_addc_u32 s3, s51, s41
	s_nop 0
	v_addc_co_u32_e32 v3, vcc, 0, v3, vcc
	v_add_u32_e32 v10, -1, v229
	v_and_b32_e32 v3, 64, v229
	s_add_u32 s2, s48, s40
	s_addc_u32 s3, s49, s41
	s_waitcnt vmcnt(0)
	s_mov_b32 s2, 0xbfb8aa3b
	s_mov_b32 s3, 0x3f2aaaab
	v_cmp_lt_i32_e32 vcc, v10, v3
	s_mov_b32 s26, 0x3f317218
	v_mov_b32_e32 v7, 0x3ecc95a3
	v_cndmask_b32_e32 v10, v10, v229, vcc
	s_mov_b32 s27, 0x7f800000
	v_mov_b32_e32 v8, 0x7fc00000
	v_mov_b32_e32 v9, 0xff800000
	s_mov_b32 s28, 0x33800000
	v_lshlrev_b32_e32 v10, 2, v10
	v_mul_f32_e32 v2, 0xbfb8aa3b, v201
	v_exp_f32_e32 v2, v2
	v_add_f32_e32 v4, v200, v202
	v_mul_f32_e64 v5, |v4|, s2
	v_exp_f32_e32 v11, v5
	v_max_f32_e32 v12, 0, v4
	v_mul_f32_e32 v4, 0x3fb8aa3b, v203
	v_exp_f32_e32 v6, v4
	v_add_f32_e32 v13, 1.0, v11
	v_add_f32_e32 v14, -1.0, v13
	v_frexp_mant_f32_e32 v15, v13
	v_cvt_f64_f32_e32 v[4:5], v13
	v_sub_f32_e32 v16, v14, v13
	v_frexp_exp_i32_f64_e32 v4, v[4:5]
	v_cmp_gt_f32_e32 vcc, s3, v15
	v_sub_f32_e32 v14, v11, v14
	v_add_f32_e32 v5, 1.0, v16
	v_subbrev_co_u32_e32 v4, vcc, 0, v4, vcc
	v_add_f32_e32 v5, v14, v5
	v_sub_u32_e32 v14, 0, v4
	v_cvt_f32_i32_e32 v4, v4
	v_ldexp_f32 v13, v13, v14
	v_ldexp_f32 v5, v5, v14
	v_add_f32_e32 v14, -1.0, v13
	v_add_f32_e32 v15, 1.0, v13
	v_add_f32_e32 v16, 1.0, v14
	v_add_f32_e32 v17, -1.0, v15
	v_sub_f32_e32 v16, v13, v16
	v_sub_f32_e32 v13, v13, v17
	v_mul_f32_e32 v17, 0x3f317218, v4
	v_add_f32_e32 v16, v5, v16
	v_add_f32_e32 v5, v5, v13
	v_fma_f32 v13, v4, s26, -v17
	v_add_f32_e32 v18, v14, v16
	v_add_f32_e32 v19, v15, v5
	v_fmac_f32_e32 v13, 0xb102e308, v4
	v_sub_f32_e32 v4, v18, v14
	v_sub_f32_e32 v14, v19, v15
	v_rcp_f32_e32 v15, v19
	v_add_f32_e32 v20, v17, v13
	v_sub_f32_e32 v5, v5, v14
	v_sub_f32_e32 v14, v20, v17
	v_sub_f32_e32 v13, v13, v14
	v_mul_f32_e32 v14, v18, v15
	v_sub_f32_e32 v4, v16, v4
	v_mul_f32_e32 v16, v19, v14
	v_fma_f32 v17, v14, v19, -v16
	v_fmac_f32_e32 v17, v14, v5
	v_add_f32_e32 v21, v16, v17
	v_sub_f32_e32 v22, v18, v21
	v_sub_f32_e32 v16, v21, v16
	v_sub_f32_e32 v18, v18, v22
	v_sub_f32_e32 v16, v16, v17
	v_sub_f32_e32 v17, v18, v21
	v_add_f32_e32 v4, v4, v17
	v_add_f32_e32 v4, v16, v4
	v_add_f32_e32 v16, v22, v4
	v_mul_f32_e32 v17, v15, v16
	v_sub_f32_e32 v18, v22, v16
	v_mul_f32_e32 v21, v19, v17
	v_add_f32_e32 v4, v4, v18
	v_add_f32_e32 v18, v14, v17
	v_fma_f32 v19, v17, v19, -v21
	v_sub_f32_e32 v14, v18, v14
	v_fmac_f32_e32 v19, v17, v5
	v_sub_f32_e32 v5, v17, v14
	v_add_f32_e32 v14, v21, v19
	v_sub_f32_e32 v17, v14, v21
	v_sub_f32_e32 v21, v16, v14
	v_sub_f32_e32 v16, v16, v21
	v_sub_f32_e32 v14, v16, v14
	v_sub_f32_e32 v17, v17, v19
	v_add_f32_e32 v4, v4, v14
	v_add_f32_e32 v4, v17, v4
	v_add_f32_e32 v4, v21, v4
	v_mul_f32_e32 v4, v15, v4
	v_add_f32_e32 v4, v5, v4
	v_add_f32_e32 v5, v18, v4
	v_mul_f32_e32 v14, v5, v5
	v_fmamk_f32 v7, v14, 0x3e9b6dac, v7
	v_sub_f32_e32 v15, v5, v18
	v_ldexp_f32 v16, v5, 1
	v_mul_f32_e32 v5, v5, v14
	v_fmaak_f32 v7, v14, v7, 0x3f2aaada
	v_mul_f32_e32 v5, v5, v7
	v_add_f32_e32 v7, v16, v5
	v_sub_f32_e32 v4, v4, v15
	v_sub_f32_e32 v14, v7, v16
	v_ldexp_f32 v4, v4, 1
	v_sub_f32_e32 v5, v5, v14
	v_add_f32_e32 v4, v4, v5
	v_add_f32_e32 v5, v7, v4
	v_sub_f32_e32 v7, v5, v7
	v_add_f32_e32 v14, v20, v5
	v_sub_f32_e32 v4, v4, v7
	v_sub_f32_e32 v7, v14, v20
	v_sub_f32_e32 v15, v14, v7
	v_sub_f32_e32 v5, v5, v7
	v_add_f32_e32 v7, v13, v4
	v_sub_f32_e32 v15, v20, v15
	v_sub_f32_e32 v16, v7, v13
	v_add_f32_e32 v5, v5, v15
	v_sub_f32_e32 v15, v7, v16
	v_add_f32_e32 v5, v7, v5
	v_sub_f32_e32 v4, v4, v16
	v_sub_f32_e32 v13, v13, v15
	v_add_f32_e32 v7, v14, v5
	v_add_f32_e32 v4, v4, v13
	v_sub_f32_e32 v13, v7, v14
	v_sub_f32_e32 v5, v5, v13
	v_add_f32_e32 v4, v4, v5
	v_add_f32_e32 v4, v7, v4
	v_cmp_neq_f32_e32 vcc, s27, v11
	v_add_f32_e32 v2, 1.0, v2
	s_nop 0
	v_cndmask_b32_e32 v4, v228, v4, vcc
	v_cmp_ngt_f32_e32 vcc, -1.0, v11
	s_nop 1
	v_cndmask_b32_e32 v4, v8, v4, vcc
	v_cmp_neq_f32_e32 vcc, -1.0, v11
	v_add_u32_e32 v8, -2, v229
	s_nop 0
	v_cndmask_b32_e32 v4, v9, v4, vcc
	v_cmp_lt_f32_e64 vcc, |v11|, s28
	s_nop 1
	v_cndmask_b32_e32 v4, v4, v11, vcc
	v_add_f32_e32 v4, v12, v4
	v_mul_f32_e64 v5, v4, -v6
	ds_bpermute_b32 v7, v10, v5
	v_cmp_lt_i32_e32 vcc, v8, v3
	s_waitcnt lgkmcnt(0)
	v_fma_f32 v4, v4, -v6, v7
	v_cndmask_b32_e32 v8, v8, v229, vcc
	v_cmp_eq_u32_e32 vcc, 0, v34
	v_lshlrev_b32_e32 v8, 2, v8
	v_add_u32_e32 v6, -4, v229
	v_cndmask_b32_e32 v4, v4, v5, vcc
	ds_bpermute_b32 v5, v8, v4
	v_cmp_lt_i32_e32 vcc, v6, v3
	s_waitcnt lgkmcnt(0)
	v_add_f32_e32 v5, v4, v5
	v_cndmask_b32_e32 v6, v6, v229, vcc
	v_cmp_gt_u32_e32 vcc, 2, v34
	s_nop 1
	v_cndmask_b32_e32 v4, v5, v4, vcc
	v_lshlrev_b32_e32 v5, 2, v6
	ds_bpermute_b32 v5, v5, v4
	v_add_u32_e32 v6, -8, v229
	v_cmp_gt_u32_e32 vcc, 4, v34
	s_waitcnt lgkmcnt(0)
	v_add_f32_e32 v5, v4, v5
	v_cndmask_b32_e32 v4, v5, v4, vcc
	v_cmp_lt_i32_e32 vcc, v6, v3
	s_nop 1
	v_cndmask_b32_e32 v5, v6, v229, vcc
	v_lshlrev_b32_e32 v5, 2, v5
	ds_bpermute_b32 v5, v5, v4
	v_add_u32_e32 v6, -16, v229
	v_cmp_gt_u32_e32 vcc, 8, v34
	s_waitcnt lgkmcnt(0)
	v_add_f32_e32 v5, v4, v5
	v_cndmask_b32_e32 v4, v5, v4, vcc
	v_cmp_lt_i32_e32 vcc, v6, v3
	s_nop 1
	v_cndmask_b32_e32 v5, v6, v229, vcc
	v_lshlrev_b32_e32 v5, 2, v5
	ds_bpermute_b32 v5, v5, v4
	v_cmp_gt_u32_e32 vcc, 16, v34
	s_waitcnt lgkmcnt(0)
	v_add_f32_e32 v5, v4, v5
	v_cndmask_b32_e32 v4, v5, v4, vcc
	v_subrev_u32_e32 v5, 32, v229
	v_cmp_lt_i32_e32 vcc, v5, v3
	s_nop 1
	v_cndmask_b32_e32 v3, v5, v229, vcc
	v_lshlrev_b32_e32 v3, 2, v3
	ds_bpermute_b32 v3, v3, v4
	v_cmp_gt_u32_e32 vcc, 32, v34
	v_add_u32_e32 v5, 0x10300, v1
	s_waitcnt lgkmcnt(0)
	v_add_f32_e32 v3, v4, v3
	v_cndmask_b32_e32 v3, v3, v4, vcc
	v_rcp_f32_e32 v4, v2
	v_mul_f32_e32 v2, 0x3fb8aa3b, v3
	v_exp_f32_e32 v2, v2
	ds_write_b32 v5, v3
	v_add_u32_e32 v3, 0x10400, v1
	ds_write_b32 v3, v4
	v_add_u32_e32 v3, 0x10500, v1
	ds_write_b32 v3, v2
	v_mul_f32_e32 v3, v4, v2
	v_add_u32_e32 v4, 0x10600, v1
	v_cmp_eq_u32_e32 vcc, 63, v68
	ds_write_b32 v4, v3
	s_and_b64 exec, exec, vcc
	s_cbranch_execz .LBB0_368
	s_lshl_b64 s[2:3], s[86:87], 2
	s_add_u32 s2, s80, s2
	s_addc_u32 s3, s81, s3
	global_store_dword v225, v2, s[2:3]
.LBB0_368:
	s_setprio 0
	s_or_b64 exec, exec, s[46:47]
	s_movk_i32 s2, 0x80
	v_cmp_gt_i32_e64 s[46:47], s2, v68
	s_waitcnt lgkmcnt(0)
	s_barrier
	s_and_saveexec_b64 s[40:41], s[46:47]
	s_cbranch_execz .LBB0_373
	v_cndmask_b32_e64 v2, v230, 0, s[44:45]
	s_mov_b32 s26, 0
	v_mad_u32_u24 v4, v34, s33, v2
	v_mov_b32_e32 v2, 0
